# hand-written grid barrier at 7 sites: arrive on XCD counter, release directly through global generation word (no per-XCD release hop)
# speedup vs baseline: 1.0080x; 1.0080x over previous
.LBB0_183:
	s_mov_b32 s0, s78
	s_cmpk_eq_i32 s0, 0x100
	s_cselect_b64 s[0:1], -1, 0
	s_and_b64 s[0:1], s[10:11], s[0:1]
	s_and_b64 vcc, exec, s[0:1]
	s_cbranch_vccnz .LBB0_237
	s_mov_b64 s[12:13], s[76:77]
	s_getreg_b32 s14, hwreg(HW_REG_XCC_ID, 0, 4)
	s_waitcnt vmcnt(0)
	v_readlane_b32 s6, v254, 1
	v_readlane_b32 s7, v254, 2
	s_waitcnt lgkmcnt(0)
	s_barrier
	s_and_saveexec_b64 s[0:1], s[6:7]
	s_cbranch_execz .LBB0_236
	s_load_dwordx2 s[2:3], s[76:77], 0xc8
	s_getreg_b32 s9, hwreg(HW_REG_XCC_ID, 0, 4)
	v_mov_b32_e32 v2, 0x253c0
	ds_read_b64 v[0:1], v2
	v_mov_b32_e32 v2, 0
	v_mov_b32_e32 v6, 1
	s_lshl_b32 s9, s9, 8
	s_add_u32 s9, s9, 0x4000
	s_waitcnt lgkmcnt(0)
	s_add_u32 s6, s2, s9
	s_addc_u32 s7, s3, 0
	v_mov_b32_e32 v7, 0x1000
	global_atomic_add v7, v7, v6, s[6:7] offset:1024 sc0
	v_readfirstlane_b32 s12, v0
	v_readfirstlane_b32 s13, v1
	v_cvt_f32_u32_e32 v0, v0
	s_nop 0
	v_rcp_iflag_f32_e32 v0, v0
	s_waitcnt vmcnt(0)
	v_readfirstlane_b32 s14, v7
	v_cvt_f32_u32_e32 v7, v7
	s_nop 1
	v_mul_f32_e32 v7, v7, v0
	s_nop 0
	v_cvt_u32_f32_e32 v7, v7
	s_nop 1
	v_readfirstlane_b32 s15, v7
	s_mul_i32 s17, s15, s12
	s_sub_i32 s16, s14, s17
	s_cmp_lt_i32 s16, 0
	s_cbranch_scc0 .Lgb_q1_s0
	s_add_i32 s15, s15, -1
	s_add_i32 s16, s16, s12
.Lgb_q1_s0:
	s_cmp_ge_i32 s16, s12
	s_cbranch_scc0 .Lgb_q2_s0
	s_add_i32 s15, s15, 1
	s_sub_i32 s16, s16, s12
.Lgb_q2_s0:
	s_add_i32 s17, s16, 1
	s_cmp_eq_u32 s17, s12
	s_cbranch_scc0 .Lgb_wait_s0
	buffer_wbl2 sc1
	s_waitcnt vmcnt(0)
	v_mov_b32_e32 v7, 0x7000
	global_atomic_add v7, v7, v6, s[2:3] offset:1024 sc0
	s_add_i32 s17, s15, 1
	s_mul_i32 s17, s17, s13
	s_waitcnt vmcnt(0)
	v_readfirstlane_b32 s14, v7
	s_add_i32 s14, s14, 1
	s_cmp_eq_u32 s14, s17
	s_cbranch_scc0 .Lgb_wait_s0
	v_mov_b32_e32 v7, 0x7500
	global_atomic_add v7, v6, s[2:3]
	s_branch .Lgb_acq_s0
.Lgb_wait_s0:
	s_mov_b32 s18, 0
	v_mov_b32_e32 v0, 0x7500
.Lgb_spin_s0:
	global_load_dword v7, v0, s[2:3] sc1
	s_add_u32 s18, s18, 1
	s_waitcnt vmcnt(0)
	v_readfirstlane_b32 s17, v7
	s_cmp_lg_u32 s17, s15
	s_cbranch_scc1 .Lgb_acq_s0
	s_sleep 1
	s_cmp_lt_u32 s18, 0x200000
	s_cbranch_scc1 .Lgb_spin_s0
.Lgb_acq_s0:
	s_waitcnt vmcnt(0)
	buffer_inv sc1
	s_waitcnt vmcnt(0)

.LBB0_253:
	s_mov_b64 s[12:13], s[76:77]
	s_getreg_b32 s14, hwreg(HW_REG_XCC_ID, 0, 4)
	s_waitcnt vmcnt(0)
	v_readlane_b32 s6, v254, 1
	v_readlane_b32 s7, v254, 2
	s_waitcnt vmcnt(0) lgkmcnt(0)
	s_barrier
	s_and_saveexec_b64 s[0:1], s[6:7]
	s_cbranch_execz .LBB0_305
	s_load_dwordx2 s[2:3], s[76:77], 0xc8
	s_getreg_b32 s9, hwreg(HW_REG_XCC_ID, 0, 4)
	v_mov_b32_e32 v2, 0x253c0
	ds_read_b64 v[0:1], v2
	v_mov_b32_e32 v2, 0
	v_mov_b32_e32 v6, 1
	s_lshl_b32 s9, s9, 8
	s_add_u32 s9, s9, 0x4000
	s_waitcnt lgkmcnt(0)
	s_add_u32 s6, s2, s9
	s_addc_u32 s7, s3, 0
	v_mov_b32_e32 v7, 0x1000
	global_atomic_add v7, v7, v6, s[6:7] offset:1024 sc0
	v_readfirstlane_b32 s12, v0
	v_readfirstlane_b32 s13, v1
	v_cvt_f32_u32_e32 v0, v0
	s_nop 0
	v_rcp_iflag_f32_e32 v0, v0
	s_waitcnt vmcnt(0)
	v_readfirstlane_b32 s16, v7
	v_cvt_f32_u32_e32 v7, v7
	s_nop 1
	v_mul_f32_e32 v7, v7, v0
	s_nop 0
	v_cvt_u32_f32_e32 v7, v7
	s_nop 1
	v_readfirstlane_b32 s17, v7
	s_mul_i32 s19, s17, s12
	s_sub_i32 s18, s16, s19
	s_cmp_lt_i32 s18, 0
	s_cbranch_scc0 .Lgb_q1_s1
	s_add_i32 s17, s17, -1
	s_add_i32 s18, s18, s12
.Lgb_q1_s1:
	s_cmp_ge_i32 s18, s12
	s_cbranch_scc0 .Lgb_q2_s1
	s_add_i32 s17, s17, 1
	s_sub_i32 s18, s18, s12
.Lgb_q2_s1:
	s_add_i32 s19, s18, 1
	s_cmp_eq_u32 s19, s12
	s_cbranch_scc0 .Lgb_wait_s1
	buffer_wbl2 sc1
	s_waitcnt vmcnt(0)
	v_mov_b32_e32 v7, 0x7000
	global_atomic_add v7, v7, v6, s[2:3] offset:1024 sc0
	s_add_i32 s19, s17, 1
	s_mul_i32 s19, s19, s13
	s_waitcnt vmcnt(0)
	v_readfirstlane_b32 s16, v7
	s_add_i32 s16, s16, 1
	s_cmp_eq_u32 s16, s19
	s_cbranch_scc0 .Lgb_wait_s1
	v_mov_b32_e32 v7, 0x7500
	global_atomic_add v7, v6, s[2:3]
	s_branch .Lgb_acq_s1
.Lgb_wait_s1:
	s_mov_b32 s20, 0
	v_mov_b32_e32 v0, 0x7500
.Lgb_spin_s1:
	global_load_dword v7, v0, s[2:3] sc1
	s_add_u32 s20, s20, 1
	s_waitcnt vmcnt(0)
	v_readfirstlane_b32 s19, v7
	s_cmp_lg_u32 s19, s17
	s_cbranch_scc1 .Lgb_acq_s1
	s_sleep 1
	s_cmp_lt_u32 s20, 0x200000
	s_cbranch_scc1 .Lgb_spin_s1

.LBB0_410:
	v_readlane_b32 s58, v254, 19
	v_readlane_b32 s60, v254, 17
	s_andn2_b64 vcc, exec, s[10:11]
	s_mov_b32 s37, 0x400000
	s_mov_b32 s40, 0x800000
	s_mov_b32 s41, 0xc00000
	s_mov_b32 s45, 0x1000000
	s_waitcnt lgkmcnt(0)
	s_mov_b32 s31, 0xefa18f08
	s_mov_b32 s29, 0x41000000
	v_readlane_b32 s59, v254, 20
	v_readlane_b32 s61, v254, 18
	s_cbranch_vccnz .LBB0_464
	s_mov_b64 s[4:5], s[76:77]
	s_getreg_b32 s10, hwreg(HW_REG_XCC_ID, 0, 4)
	s_waitcnt vmcnt(0)
	v_readlane_b32 s6, v254, 1
	v_readlane_b32 s7, v254, 2
	s_waitcnt vmcnt(0)
	s_barrier
	s_and_saveexec_b64 s[0:1], s[6:7]
	s_cbranch_execz .LBB0_463
	s_load_dwordx2 s[4:5], s[76:77], 0xc8
	s_getreg_b32 s9, hwreg(HW_REG_XCC_ID, 0, 4)
	v_mov_b32_e32 v2, 0x253c0
	ds_read_b64 v[0:1], v2
	v_mov_b32_e32 v2, 0
	v_mov_b32_e32 v6, 1
	s_lshl_b32 s9, s9, 8
	s_add_u32 s9, s9, 0x4000
	s_waitcnt lgkmcnt(0)
	s_add_u32 s6, s4, s9
	s_addc_u32 s7, s5, 0
	v_mov_b32_e32 v7, 0x1000
	global_atomic_add v7, v7, v6, s[6:7] offset:1024 sc0
	v_readfirstlane_b32 s10, v0
	v_readfirstlane_b32 s11, v1
	v_cvt_f32_u32_e32 v0, v0
	s_nop 0
	v_rcp_iflag_f32_e32 v0, v0
	s_waitcnt vmcnt(0)
	v_readfirstlane_b32 s12, v7
	v_cvt_f32_u32_e32 v7, v7
	s_nop 1
	v_mul_f32_e32 v7, v7, v0
	s_nop 0
	v_cvt_u32_f32_e32 v7, v7
	s_nop 1
	v_readfirstlane_b32 s13, v7
	s_mul_i32 s15, s13, s10
	s_sub_i32 s14, s12, s15
	s_cmp_lt_i32 s14, 0
	s_cbranch_scc0 .Lgb_q1_s2
	s_add_i32 s13, s13, -1
	s_add_i32 s14, s14, s10
.Lgb_q1_s2:
	s_cmp_ge_i32 s14, s10
	s_cbranch_scc0 .Lgb_q2_s2
	s_add_i32 s13, s13, 1
	s_sub_i32 s14, s14, s10
.Lgb_q2_s2:
	s_add_i32 s15, s14, 1
	s_cmp_eq_u32 s15, s10
	s_cbranch_scc0 .Lgb_wait_s2
	buffer_wbl2 sc1
	s_waitcnt vmcnt(0)
	v_mov_b32_e32 v7, 0x7000
	global_atomic_add v7, v7, v6, s[4:5] offset:1024 sc0
	s_add_i32 s15, s13, 1
	s_mul_i32 s15, s15, s11
	s_waitcnt vmcnt(0)
	v_readfirstlane_b32 s12, v7
	s_add_i32 s12, s12, 1
	s_cmp_eq_u32 s12, s15
	s_cbranch_scc0 .Lgb_wait_s2
	v_mov_b32_e32 v7, 0x7500
	global_atomic_add v7, v6, s[4:5]
	s_branch .Lgb_acq_s2

.Lgb_spin_s2:
	global_load_dword v7, v0, s[4:5] sc1
	s_add_u32 s18, s18, 1
	s_waitcnt vmcnt(0)
	v_readfirstlane_b32 s15, v7
	s_cmp_lg_u32 s15, s13
	s_cbranch_scc1 .Lgb_acq_s2
	s_sleep 1
	s_cmp_lt_u32 s18, 0x200000
	s_cbranch_scc1 .Lgb_spin_s2

.LBB0_504:
	s_waitcnt lgkmcnt(0)
	s_mov_b64 s[2:3], s[76:77]
	s_getreg_b32 s4, hwreg(HW_REG_XCC_ID, 0, 4)
	s_waitcnt vmcnt(0)
	s_waitcnt vmcnt(0)
	s_barrier
	s_mov_b64 s[0:1], exec
	v_readlane_b32 s6, v254, 1
	v_readlane_b32 s7, v254, 2
	s_and_b64 s[6:7], s[0:1], s[6:7]
	s_mov_b64 exec, s[6:7]
	s_cbranch_execz .LBB0_556
	s_load_dwordx2 s[2:3], s[76:77], 0xc8
	s_getreg_b32 s6, hwreg(HW_REG_XCC_ID, 0, 4)
	v_mov_b32_e32 v2, 0x253c0
	ds_read_b64 v[0:1], v2
	v_mov_b32_e32 v2, 0
	v_mov_b32_e32 v6, 1
	s_lshl_b32 s6, s6, 8
	s_add_u32 s6, s6, 0x4000
	s_waitcnt lgkmcnt(0)
	s_add_u32 s4, s2, s6
	s_addc_u32 s5, s3, 0
	v_mov_b32_e32 v7, 0x1000
	global_atomic_add v7, v7, v6, s[4:5] offset:1024 sc0
	v_readfirstlane_b32 s7, v0
	v_readfirstlane_b32 s9, v1
	v_cvt_f32_u32_e32 v0, v0
	s_nop 0
	v_rcp_iflag_f32_e32 v0, v0
	s_waitcnt vmcnt(0)
	v_readfirstlane_b32 s10, v7
	v_cvt_f32_u32_e32 v7, v7
	s_nop 1
	v_mul_f32_e32 v7, v7, v0
	s_nop 0
	v_cvt_u32_f32_e32 v7, v7
	s_nop 1
	v_readfirstlane_b32 s11, v7
	s_mul_i32 s13, s11, s7
	s_sub_i32 s12, s10, s13
	s_cmp_lt_i32 s12, 0
	s_cbranch_scc0 .Lgb_q1_s3
	s_add_i32 s11, s11, -1
	s_add_i32 s12, s12, s7
.Lgb_q1_s3:
	s_cmp_ge_i32 s12, s7
	s_cbranch_scc0 .Lgb_q2_s3
	s_add_i32 s11, s11, 1
	s_sub_i32 s12, s12, s7
.Lgb_q2_s3:
	s_add_i32 s13, s12, 1
	s_cmp_eq_u32 s13, s7
	s_cbranch_scc0 .Lgb_wait_s3
	buffer_wbl2 sc1
	s_waitcnt vmcnt(0)
	v_mov_b32_e32 v7, 0x7000
	global_atomic_add v7, v7, v6, s[2:3] offset:1024 sc0
	s_add_i32 s13, s11, 1
	s_mul_i32 s13, s13, s9
	s_waitcnt vmcnt(0)
	v_readfirstlane_b32 s10, v7
	s_add_i32 s10, s10, 1
	s_cmp_eq_u32 s10, s13
	s_cbranch_scc0 .Lgb_wait_s3
	v_mov_b32_e32 v7, 0x7500
	global_atomic_add v7, v6, s[2:3]
	s_branch .Lgb_acq_s3
.Lgb_wait_s3:
	s_mov_b32 s14, 0
	v_mov_b32_e32 v0, 0x7500
.Lgb_spin_s3:
	global_load_dword v7, v0, s[2:3] sc1
	s_add_u32 s14, s14, 1
	s_waitcnt vmcnt(0)
	v_readfirstlane_b32 s13, v7
	s_cmp_lg_u32 s13, s11
	s_cbranch_scc1 .Lgb_acq_s3
	s_sleep 1
	s_cmp_lt_u32 s14, 0x200000
	s_cbranch_scc1 .Lgb_spin_s3

.LBB0_660:
	s_waitcnt lgkmcnt(0)
	s_mov_b64 s[2:3], s[76:77]
	s_getreg_b32 s4, hwreg(HW_REG_XCC_ID, 0, 4)
	s_waitcnt vmcnt(0)
	s_waitcnt vmcnt(0)
	s_barrier
	s_mov_b64 s[0:1], exec
	v_readlane_b32 s6, v254, 1
	v_readlane_b32 s7, v254, 2
	s_and_b64 s[6:7], s[0:1], s[6:7]
	s_mov_b32 s58, 0x3fb8aa3b
	s_mov_b64 exec, s[6:7]
	s_cbranch_execz .LBB0_712
	s_load_dwordx2 s[2:3], s[76:77], 0xc8
	s_getreg_b32 s6, hwreg(HW_REG_XCC_ID, 0, 4)
	v_mov_b32_e32 v2, 0x253c0
	ds_read_b64 v[0:1], v2
	v_mov_b32_e32 v2, 0
	v_mov_b32_e32 v3, 1
	s_lshl_b32 s6, s6, 8
	s_add_u32 s6, s6, 0x4000
	s_waitcnt lgkmcnt(0)
	s_add_u32 s4, s2, s6
	s_addc_u32 s5, s3, 0
	v_mov_b32_e32 v6, 0x1000
	global_atomic_add v6, v6, v3, s[4:5] offset:1024 sc0
	v_readfirstlane_b32 s7, v0
	v_readfirstlane_b32 s8, v1
	v_cvt_f32_u32_e32 v0, v0
	s_nop 0
	v_rcp_iflag_f32_e32 v0, v0
	s_waitcnt vmcnt(0)
	v_readfirstlane_b32 s9, v6
	v_cvt_f32_u32_e32 v6, v6
	s_nop 1
	v_mul_f32_e32 v6, v6, v0
	s_nop 0
	v_cvt_u32_f32_e32 v6, v6
	s_nop 1
	v_readfirstlane_b32 s10, v6
	s_mul_i32 s12, s10, s7
	s_sub_i32 s11, s9, s12
	s_cmp_lt_i32 s11, 0
	s_cbranch_scc0 .Lgb_q1_s4
	s_add_i32 s10, s10, -1
	s_add_i32 s11, s11, s7
.Lgb_q1_s4:
	s_cmp_ge_i32 s11, s7
	s_cbranch_scc0 .Lgb_q2_s4
	s_add_i32 s10, s10, 1
	s_sub_i32 s11, s11, s7
.Lgb_q2_s4:
	s_add_i32 s12, s11, 1
	s_cmp_eq_u32 s12, s7
	s_cbranch_scc0 .Lgb_wait_s4
	buffer_wbl2 sc1
	s_waitcnt vmcnt(0)
	v_mov_b32_e32 v6, 0x7000
	global_atomic_add v6, v6, v3, s[2:3] offset:1024 sc0
	s_add_i32 s12, s10, 1
	s_mul_i32 s12, s12, s8
	s_waitcnt vmcnt(0)
	v_readfirstlane_b32 s9, v6
	s_add_i32 s9, s9, 1
	s_cmp_eq_u32 s9, s12
	s_cbranch_scc0 .Lgb_wait_s4
	v_mov_b32_e32 v6, 0x7500
	global_atomic_add v6, v3, s[2:3]
	s_branch .Lgb_acq_s4
.Lgb_wait_s4:
	s_mov_b32 s13, 0
	v_mov_b32_e32 v0, 0x7500
.Lgb_spin_s4:
	global_load_dword v6, v0, s[2:3] sc1
	s_add_u32 s13, s13, 1
	s_waitcnt vmcnt(0)
	v_readfirstlane_b32 s12, v6
	s_cmp_lg_u32 s12, s10
	s_cbranch_scc1 .Lgb_acq_s4
	s_sleep 1
	s_cmp_lt_u32 s13, 0x200000
	s_cbranch_scc1 .Lgb_spin_s4

.LBB0_845:
	s_mov_b64 s[2:3], s[76:77]
	s_getreg_b32 s4, hwreg(HW_REG_XCC_ID, 0, 4)
	s_waitcnt vmcnt(0)
	s_waitcnt lgkmcnt(0)
	s_barrier
	s_mov_b64 s[0:1], exec
	v_readlane_b32 s6, v254, 1
	v_readlane_b32 s7, v254, 2
	s_and_b64 s[6:7], s[0:1], s[6:7]
	s_mov_b64 exec, s[6:7]
	s_cbranch_execz .LBB0_897
	s_load_dwordx2 s[2:3], s[76:77], 0xc8
	s_getreg_b32 s6, hwreg(HW_REG_XCC_ID, 0, 4)
	v_mov_b32_e32 v2, 0x253c0
	ds_read_b64 v[0:1], v2
	v_mov_b32_e32 v2, 0
	v_mov_b32_e32 v6, 1
	s_lshl_b32 s6, s6, 8
	s_add_u32 s6, s6, 0x4000
	s_waitcnt lgkmcnt(0)
	s_add_u32 s4, s2, s6
	s_addc_u32 s5, s3, 0
	v_mov_b32_e32 v7, 0x1000
	global_atomic_add v7, v7, v6, s[4:5] offset:1024 sc0
	v_readfirstlane_b32 s7, v0
	v_readfirstlane_b32 s8, v1
	v_cvt_f32_u32_e32 v0, v0
	s_nop 0
	v_rcp_iflag_f32_e32 v0, v0
	s_waitcnt vmcnt(0)
	v_readfirstlane_b32 s9, v7
	v_cvt_f32_u32_e32 v7, v7
	s_nop 1
	v_mul_f32_e32 v7, v7, v0
	s_nop 0
	v_cvt_u32_f32_e32 v7, v7
	s_nop 1
	v_readfirstlane_b32 s10, v7
	s_mul_i32 s12, s10, s7
	s_sub_i32 s11, s9, s12
	s_cmp_lt_i32 s11, 0
	s_cbranch_scc0 .Lgb_q1_s5
	s_add_i32 s10, s10, -1
	s_add_i32 s11, s11, s7

.Lgb_q2_s5:
	s_add_i32 s12, s11, 1
	s_cmp_eq_u32 s12, s7
	s_cbranch_scc0 .Lgb_wait_s5
	buffer_wbl2 sc1
	s_waitcnt vmcnt(0)
	v_mov_b32_e32 v7, 0x7000
	global_atomic_add v7, v7, v6, s[2:3] offset:1024 sc0
	s_add_i32 s12, s10, 1
	s_mul_i32 s12, s12, s8
	s_waitcnt vmcnt(0)
	v_readfirstlane_b32 s9, v7
	s_add_i32 s9, s9, 1
	s_cmp_eq_u32 s9, s12
	s_cbranch_scc0 .Lgb_wait_s5
	v_mov_b32_e32 v7, 0x7500
	global_atomic_add v7, v6, s[2:3]
	s_branch .Lgb_acq_s5

.Lgb_spin_s5:
	global_load_dword v7, v0, s[2:3] sc1
	s_add_u32 s13, s13, 1
	s_waitcnt vmcnt(0)
	v_readfirstlane_b32 s12, v7
	s_cmp_lg_u32 s12, s10
	s_cbranch_scc1 .Lgb_acq_s5
	s_sleep 1
	s_cmp_lt_u32 s13, 0x200000
	s_cbranch_scc1 .Lgb_spin_s5

.LBB0_980:
	s_load_dwordx2 s[2:3], s[76:77], 0xc8
	s_getreg_b32 s9, hwreg(HW_REG_XCC_ID, 0, 4)
	v_mov_b32_e32 v2, 0x253c0
	ds_read_b64 v[0:1], v2
	v_mov_b32_e32 v2, 0
	v_mov_b32_e32 v6, 1
	s_lshl_b32 s9, s9, 8
	s_add_u32 s9, s9, 0x4000
	s_waitcnt lgkmcnt(0)
	s_add_u32 s4, s2, s9
	s_addc_u32 s5, s3, 0
	v_mov_b32_e32 v7, 0x1000
	global_atomic_add v7, v7, v6, s[4:5] offset:1024 sc0
	v_readfirstlane_b32 s10, v0
	v_readfirstlane_b32 s11, v1
	v_cvt_f32_u32_e32 v0, v0
	s_nop 0
	v_rcp_iflag_f32_e32 v0, v0
	s_waitcnt vmcnt(0)
	v_readfirstlane_b32 s12, v7
	v_cvt_f32_u32_e32 v7, v7
	s_nop 1
	v_mul_f32_e32 v7, v7, v0
	s_nop 0
	v_cvt_u32_f32_e32 v7, v7
	s_nop 1
	v_readfirstlane_b32 s13, v7
	s_mul_i32 s15, s13, s10
	s_sub_i32 s14, s12, s15
	s_cmp_lt_i32 s14, 0
	s_cbranch_scc0 .Lgb_q1_s6
	s_add_i32 s13, s13, -1
	s_add_i32 s14, s14, s10

.Lgb_q2_s6:
	s_add_i32 s15, s14, 1
	s_cmp_eq_u32 s15, s10
	s_cbranch_scc0 .Lgb_wait_s6
	buffer_wbl2 sc1
	s_waitcnt vmcnt(0)
	v_mov_b32_e32 v7, 0x7000
	global_atomic_add v7, v7, v6, s[2:3] offset:1024 sc0
	s_add_i32 s15, s13, 1
	s_mul_i32 s15, s15, s11
	s_waitcnt vmcnt(0)
	v_readfirstlane_b32 s12, v7
	s_add_i32 s12, s12, 1
	s_cmp_eq_u32 s12, s15
	s_cbranch_scc0 .Lgb_wait_s6
	v_mov_b32_e32 v7, 0x7500
	global_atomic_add v7, v6, s[2:3]
	s_branch .Lgb_acq_s6

.Lgb_spin_s6:
	global_load_dword v7, v0, s[2:3] sc1
	s_add_u32 s18, s18, 1
	s_waitcnt vmcnt(0)
	v_readfirstlane_b32 s15, v7
	s_cmp_lg_u32 s15, s13
	s_cbranch_scc1 .Lgb_acq_s6
	s_sleep 1
	s_cmp_lt_u32 s18, 0x200000
	s_cbranch_scc1 .Lgb_spin_s6
.Lgb_acq_s6:
	s_waitcnt vmcnt(0)
	buffer_inv sc1
	s_waitcnt vmcnt(0)
	s_getpc_b64 s[98:99]
